# dil item restructured into two passes: all (<=6) K/V tiles staged into separate LDS slots first, one barrier, then each wave runs its attention tiles without per-tile barriers
# speedup vs baseline: 1.0070x; 1.0070x over previous
; #define LAS __attribute__((address_space(3)))
; template <bool NORM> __device__ __forceinline__ void kv_store(u32x4 kc, u32x4 vc, const float (&g)[8], LAS unsigned char* ksb, LAS unsigned char* vtb, int tid) {
;     const int kl = tid >> 3, ch = tid & 7;
;     if (NORM) { UNPACK8(kc, k); float ss = (k0 * k0 + k1 * k1) + (k2 * k2 + k3 * k3) + (k4 * k4 + k5 * k5) + (k6 * k6 + k7 * k7);
;         ss += swz_f<1>(ss); ss += swz_f<2>(ss); ss += swz_f<4>(ss);
;         const float rs = rsqrtf(ss * (1.f / 64.f) + EPS);
;         kc.x = cvtpk(k0 * rs * g[0], k1 * rs * g[1]); kc.y = cvtpk(k2 * rs * g[2], k3 * rs * g[3]); kc.z = cvtpk(k4 * rs * g[4], k5 * rs * g[5]); kc.w = cvtpk(k6 * rs * g[6], k7 * rs * g[7]); }
;     *(LAS u32x4*)(ksb + kl * KSB + ch * 16) = kc;
;     LAS unsigned short* vp = (LAS unsigned short*)(vtb + (8 * ch) * VTB + kl * 2);
;     vp[0 * (VTB / 2)] = (unsigned short)(vc.x & 0xffffu); vp[1 * (VTB / 2)] = (unsigned short)(vc.x >> 16);
;     vp[2 * (VTB / 2)] = (unsigned short)(vc.y & 0xffffu); vp[3 * (VTB / 2)] = (unsigned short)(vc.y >> 16);
;     vp[4 * (VTB / 2)] = (unsigned short)(vc.z & 0xffffu); vp[5 * (VTB / 2)] = (unsigned short)(vc.z >> 16);
; __device__ __forceinline__ void dil_item(const DilArgs& A, int item, LAS unsigned char* lds, int tid) {
;     ...
;     const int dil = cfg == 0 ? 1 : (cfg == 1 ? 4 : 16), nq = 16 / dil, c = sub / nq, qt = sub % nq, i0 = 256 * qt, L = SEQ / dil;
;     const int lane = tid & 63, w = __builtin_amdgcn_readfirstlane(tid >> 6), r = lane & 31, hh = lane >> 5;
;     const int iq = i0 + 32 * w + r, tq = c + dil * iq; const size_t token = (size_t)b * SEQ + tq;
;     const bf16_t* base = A.proj + (size_t)b * SEQ * NP;
;     const float slope = exp2f(-(float)(2 * head + 2)) * (float)dil * LOG2E;
;     bf16x8 qf[4]; load_qfrag<true>(qf, base + (size_t)tq * NP + C_QD + head * 64, A.g_q, nullptr, 0.125f * LOG2E, hh);
;     const bf16_t* kp = base + (size_t)c * NP + C_KD + head * 64; const bf16_t* vp = base + (size_t)c * NP + C_VD + head * 64;
;     const int kb_lo = (i0 >> 6) >= 2 ? (i0 >> 6) - 2 : 0, kb_hi = (i0 >> 6) + 3, q_lo = i0 + 32 * w;
;     f32x16 o0, o1;
; #pragma unroll
;     for (int i = 0; i < 16; ++i) { o0[i] = 0.f; o1[i] = 0.f; }
;     float m = -INFINITY, l = 0.f, dummy = 0.f;
;     KV_PIPELINE(kb_lo, (cur + 1 <= kb_hi ? cur + 1 : -1), (KVSrc{kp, vp, (long)dil * NP, 64 * id, 0, L}), true, A.g_k,
.LBB0_862:
	s_or_b64 exec, exec, s[4:5]
	v_rsq_f32_e32 v80, v80
	s_or_b32 s24, s36, 3
	v_mul_u32_u24_e32 v111, 0x90, v21
	v_bfe_u32 v109, v21, 2, 2
	v_lshl_add_u32 v109, v106, 2, v109
	v_mul_u32_u24_e32 v112, 0xc0, v109
	v_bfe_u32 v109, v21, 4, 1
	v_lshl_add_u32 v112, v109, 5, v112
	v_and_b32_e32 v109, 3, v21
	v_lshl_add_u32 v112, v109, 3, v112
	v_mul_f32_e32 v81, 0x45800000, v80
	v_cndmask_b32_e64 v80, v80, v81, s[0:1]
	v_mul_f32_e32 v88, 0x3e38aa3b, v80
	v_pk_mul_f32 v[16:17], v[88:89], v[16:17] op_sel_hi:[0,1]
	s_waitcnt vmcnt(0)
	v_pk_mul_f32 v[16:17], v[16:17], v[22:23]
	v_pk_mul_f32 v[10:11], v[88:89], v[10:11] op_sel_hi:[0,1]
	v_pk_mul_f32 v[22:23], v[10:11], v[26:27]
	v_cvt_pk_bf16_f32 v10, v16, v17
	v_mul_f32_e32 v16, v88, v54
	v_mul_f32_e32 v17, v88, v53
	v_mul_f32_e32 v16, v16, v78
	v_mul_f32_e32 v17, v17, v77
	v_cvt_pk_bf16_f32 v83, v16, v17
	v_mul_f32_e32 v16, v88, v46
	v_mul_f32_e32 v17, v88, v45
	s_and_b64 s[0:1], s[6:7], exec
	v_mul_f32_e32 v16, v16, v70
	v_mul_f32_e32 v17, v17, v69
	s_cselect_b32 s4, 4, 16
	s_and_b64 s[0:1], s[8:9], exec
	v_cvt_pk_bf16_f32 v87, v16, v17
	v_mul_f32_e32 v16, v88, v38
	v_mul_f32_e32 v17, v88, v37
	s_cselect_b32 s4, 1, s4
	s_lshl_b32 s0, s15, 1
	v_mul_f32_e32 v16, v16, v62
	v_mul_f32_e32 v17, v17, v61
	s_add_i32 s0, s0, 2
	v_cvt_pk_bf16_f32 v91, v16, v17
	v_cvt_f32_ubyte0_e32 v16, s0
	s_mov_b32 s0, 0x42fc0000
	v_cmp_lt_f32_e32 vcc, s0, v16
	s_and_b64 s[0:1], vcc, exec
	v_pk_mul_f32 v[18:19], v[88:89], v[18:19] op_sel_hi:[0,1]
	v_cndmask_b32_e32 v17, 0, v214, vcc
	v_sub_f32_e32 v16, v17, v16
	v_exp_f32_e32 v16, v16
	v_pk_mul_f32 v[12:13], v[88:89], v[12:13] op_sel_hi:[0,1]
	s_cselect_b32 s0, 0xffffffc0, 0
	v_pk_mul_f32 v[12:13], v[12:13], v[24:25]
	v_pk_mul_f32 v[18:19], v[18:19], v[28:29]
	v_ldexp_f32 v16, v16, s0
	v_cvt_f32_ubyte0_e32 v17, s4
	v_cvt_pk_bf16_f32 v11, v12, v13
	v_cvt_pk_bf16_f32 v12, v22, v23
	v_cvt_pk_bf16_f32 v13, v18, v19
	v_mul_f32_e32 v18, v88, v52
	v_mul_f32_e32 v19, v88, v51
	v_mul_f32_e32 v22, v88, v50
	v_mul_f32_e32 v23, v88, v49
	v_mul_f32_e32 v24, v88, v48
	v_mul_f32_e32 v25, v88, v47
	v_mul_f32_e32 v16, v16, v17
	v_mul_f32_e32 v18, v18, v76
	v_mul_f32_e32 v19, v19, v75
	v_mul_f32_e32 v22, v22, v74
	v_mul_f32_e32 v23, v23, v73
	v_mul_f32_e32 v24, v24, v72
	v_mul_f32_e32 v25, v25, v71
	v_mul_f32_e32 v93, 0x3fb8aa3b, v16
	v_and_b32_e32 v16, 7, v30
	v_cvt_pk_bf16_f32 v80, v24, v25
	v_cvt_pk_bf16_f32 v81, v22, v23
	v_cvt_pk_bf16_f32 v82, v18, v19
	v_mul_f32_e32 v18, v88, v44
	v_mul_f32_e32 v19, v88, v43
	v_mul_f32_e32 v22, v88, v42
	v_mul_f32_e32 v23, v88, v41
	v_mul_f32_e32 v24, v88, v40
	v_mul_f32_e32 v25, v88, v39
	v_lshlrev_b32_e32 v108, 4, v16
	s_nop 0
	v_lshlrev_b32_e32 v16, 1, v20
	v_mov_b32_e32 v17, v1
	v_mul_f32_e32 v18, v18, v68
	v_mul_f32_e32 v19, v19, v67
	v_mul_f32_e32 v22, v22, v66
	v_mul_f32_e32 v23, v23, v65
	v_mul_f32_e32 v24, v24, v64
	v_mul_f32_e32 v25, v25, v63
	v_lshl_add_u64 v[102:103], s[16:17], 0, v[16:17]
	v_lshl_add_u64 v[104:105], s[26:27], 0, v[16:17]
	v_mul_i32_i24_e32 v16, -4, v106
	v_cvt_pk_bf16_f32 v84, v24, v25
	v_cvt_pk_bf16_f32 v85, v22, v23
	v_cvt_pk_bf16_f32 v86, v18, v19
	v_mul_f32_e32 v18, v88, v36
	v_mul_f32_e32 v19, v88, v35
	v_mul_f32_e32 v22, v88, v34
	v_mul_f32_e32 v23, v88, v33
	v_mul_f32_e32 v24, v88, v32
	v_mul_f32_e32 v25, v88, v31
	v_add3_u32 v16, v16, s42, v21
	v_mul_f32_e32 v18, v18, v60
	v_mul_f32_e32 v19, v19, v59
	v_mul_f32_e32 v22, v22, v58
	v_mul_f32_e32 v23, v23, v57
	v_mul_f32_e32 v24, v24, v56
	v_mul_f32_e32 v25, v25, v55
	v_subrev_u32_e32 v16, s43, v16
	v_mov_b32_e32 v30, v1
	v_mov_b32_e32 v31, v1
	v_cvt_pk_bf16_f32 v88, v24, v25
	v_cvt_pk_bf16_f32 v89, v22, v23
	v_cvt_pk_bf16_f32 v90, v18, v19
	s_movk_i32 s0, 0x90
	v_subrev_u32_e32 v113, 27, v16
	v_mov_b32_e32 v16, v1
	v_mov_b32_e32 v18, v1
	v_mov_b32_e32 v19, v1
	v_mov_b32_e32 v20, v1
	v_mov_b32_e32 v21, v1
	v_mov_b32_e32 v22, v1
	v_mov_b32_e32 v23, v1
	v_mov_b32_e32 v24, v1
	v_mov_b32_e32 v25, v1
	v_mov_b32_e32 v26, v1
	v_mov_b32_e32 v27, v1
	v_mov_b32_e32 v28, v1
	v_mov_b32_e32 v29, v1
	v_mov_b64_e32 v[46:47], v[30:31]
	s_mov_b32 s6, 0
	s_mov_b32 s99, s13
	v_mul_lo_u32 v95, v79, s0
	v_mul_u32_u24_e32 v110, 0xc0, v79
	v_add_u32_e32 v110, v110, v108
	s_add_i32 s7, s42, 0xffffff80
	s_or_b32 s8, s42, 31
	v_add_u32_e32 v114, 64, v79
	v_mov_b32_e32 v115, 0xff800000
	v_mov_b64_e32 v[44:45], v[28:29]
	v_mov_b64_e32 v[42:43], v[26:27]
	v_mov_b64_e32 v[40:41], v[24:25]
	v_mov_b64_e32 v[38:39], v[22:23]
	v_mov_b64_e32 v[36:37], v[20:21]
	v_mov_b64_e32 v[34:35], v[18:19]
	v_mov_b64_e32 v[32:33], v[16:17]
.LBB0_863:
	s_waitcnt vmcnt(1)
	v_and_b32_e32 v53, 0xffff0000, v5
	v_and_b32_e32 v51, 0xffff0000, v4
	v_lshlrev_b32_e32 v52, 16, v5
	v_lshlrev_b32_e32 v50, 16, v4
	v_pk_mul_f32 v[48:49], v[50:51], v[50:51]
	v_and_b32_e32 v57, 0xffff0000, v2
	v_and_b32_e32 v55, 0xffff0000, v3
	v_lshlrev_b32_e32 v54, 16, v3
	v_lshlrev_b32_e32 v56, 16, v2
	v_pk_fma_f32 v[48:49], v[52:53], v[52:53], v[48:49]
	s_mul_i32 s0, s6, 0x2400
	s_mul_i32 s98, s6, 0x3000
	s_add_i32 s98, s98, 0x9000
	s_add_i32 s16, s0, 0
	v_pk_fma_f32 v[48:49], v[54:55], v[54:55], v[48:49]
	v_pk_fma_f32 v[48:49], v[56:57], v[56:57], v[48:49]
	v_add_f32_e32 v48, v48, v49
	s_lshl_b32 s0, s6, 9
	s_sub_i32 s9, s16, s0
	s_cmp_ge_u32 s13, s24
	s_cselect_b64 s[4:5], -1, 0
	s_nop 1
	v_add_f32_dpp v48, v48, v48 quad_perm:[1,0,3,2] row_mask:0xf bank_mask:0xf
	s_nop 1
	v_add_f32_dpp v48, v48, v48 quad_perm:[2,3,0,1] row_mask:0xf bank_mask:0xf
	s_nop 1
	v_add_f32_dpp v48, v48, v48 row_half_mirror row_mask:0xf bank_mask:0xf
	v_fmamk_f32 v48, v48, 0x3c800000, v139
	v_rsq_f32_e32 v58, v48
	s_nop 0
	v_pk_mul_f32 v[48:49], v[58:59], v[56:57] op_sel_hi:[0,1]
	v_pk_mul_f32 v[54:55], v[58:59], v[54:55] op_sel_hi:[0,1]
	v_pk_mul_f32 v[50:51], v[58:59], v[50:51] op_sel_hi:[0,1]
	v_pk_mul_f32 v[52:53], v[58:59], v[52:53] op_sel_hi:[0,1]
	v_pk_mul_f32 v[48:49], v[14:15], v[48:49]
	v_pk_mul_f32 v[54:55], v[96:97], v[54:55]
	v_pk_mul_f32 v[50:51], v[98:99], v[50:51]
	v_pk_mul_f32 v[52:53], v[100:101], v[52:53]
	v_cvt_pk_bf16_f32 v48, v48, v49
	v_cvt_pk_bf16_f32 v49, v54, v55
	v_cvt_pk_bf16_f32 v50, v50, v51
	v_cvt_pk_bf16_f32 v51, v52, v53
	v_add3_u32 v52, s16, v95, v108
	ds_write_b128 v52, v[48:51]
	v_add_u32_e32 v48, s98, v110
	s_and_b64 vcc, exec, s[4:5]
	s_waitcnt vmcnt(0)
	ds_write_b128 v48, v[6:9] offset:18432
	s_cbranch_vccnz .LdilA_nold
	v_add_u32_e32 v185, s43, v114
	v_cmp_lt_i32_e32 vcc, -1, v185
	v_cmp_gt_i32_e64 s[0:1], s30, v185
	s_and_b64 s[26:27], vcc, s[0:1]
	v_mov_b32_e32 v9, 0
	v_mov_b32_e32 v5, 0
	v_mov_b32_e32 v4, 0
	v_mov_b32_e32 v3, 0
	v_mov_b32_e32 v2, 0
	v_mov_b32_e32 v8, 0
	v_mov_b32_e32 v7, 0
	v_mov_b32_e32 v6, 0
	s_and_saveexec_b64 s[0:1], s[26:27]
	s_cbranch_execz .LBB0_866
	v_mad_u64_u32 v[2:3], s[26:27], s44, v185, 0
	v_lshlrev_b64 v[2:3], 1, v[2:3]
	v_lshl_add_u64 v[4:5], v[102:103], 0, v[2:3]
	v_lshl_add_u64 v[6:7], v[104:105], 0, v[2:3]
	global_load_dwordx4 v[2:5], v[4:5], off
	s_nop 0
	global_load_dwordx4 v[6:9], v[6:7], off

; __device__ __forceinline__ void dil_item(const DilArgs& A, int item, LAS unsigned char* lds, int tid) {
;     ...
;     KV_PIPELINE(kb_lo, (cur + 1 <= kb_hi ? cur + 1 : -1), (KVSrc{kp, vp, (long)dil * NP, 64 * id, 0, L}), true, A.g_k,
;         { if (64 * id + 63 >= q_lo - 128 && 64 * id <= q_lo + 31) { const SfDil sf{iq, 64 * id, slope}; attn_block<0>(qf, o0, o1, m, l, ksb, vtb, r, hh, sf, 0.f, 0.f, nullptr, 0, dummy); } });
.LdilA_nold:
	s_add_i32 s13, s13, 1
	s_add_i32 s6, s6, 1
	s_andn2_b64 vcc, exec, s[4:5]
	s_add_i32 s43, s43, 64
	s_cbranch_vccz .LdilA_done
	s_branch .LBB0_863
.LdilA_done:
	s_waitcnt lgkmcnt(0)
	s_barrier
	s_mov_b32 s13, s99
	s_lshl_b32 s43, s13, 6
	s_mov_b32 s6, 0
.LdilB_top:
	s_mul_i32 s0, s6, 0x2400
	s_add_i32 s16, s0, 0
	s_mul_i32 s98, s6, 0x3000
	s_add_i32 s98, s98, 0x9000
	s_cmp_ge_u32 s13, s24
	s_cselect_b64 s[4:5], -1, 0
	s_add_i32 s0, s43, 63
	s_cmp_lt_i32 s0, s7
	s_cselect_b64 s[0:1], -1, 0
	s_cmp_gt_i32 s43, s8
	s_cselect_b64 s[26:27], -1, 0
	s_or_b64 s[100:101], s[0:1], s[26:27]
	s_cmp_lg_u64 s[100:101], 0
	s_cbranch_scc1 .Ldil_noK
	v_add3_u32 v56, s16, v111, v0
	ds_read_b128 v[48:51], v56
	ds_read_b128 v[116:119], v56 offset:32
	ds_read_b128 v[52:55], v56 offset:4608
	ds_read_b128 v[120:123], v56 offset:4640
	ds_read_b128 v[190:193], v56 offset:64
	ds_read_b128 v[194:197], v56 offset:96
	ds_read_b128 v[198:201], v56 offset:4672
	ds_read_b128 v[202:205], v56 offset:4704
.Ldil_noK:
.LBB0_867:
	s_add_i32 s0, s43, 63
	s_cmp_lt_i32 s0, s7
	s_cselect_b64 s[0:1], -1, 0
	s_cmp_gt_i32 s43, s8
	s_cselect_b64 s[26:27], -1, 0
	s_or_b64 s[0:1], s[0:1], s[26:27]
	s_and_b64 vcc, exec, s[0:1]
	s_cbranch_vccnz .LBB0_871
	s_setprio 1
	s_waitcnt lgkmcnt(7)
	v_mfma_f32_32x32x16_bf16 v[64:79], v[48:51], v[88:91], 0
	s_waitcnt lgkmcnt(5)
	v_mfma_f32_32x32x16_bf16 v[48:63], v[52:55], v[88:91], 0
	v_mfma_f32_32x32x16_bf16 v[64:79], v[116:119], v[84:87], v[64:79]
	s_waitcnt lgkmcnt(4)
	v_mfma_f32_32x32x16_bf16 v[48:63], v[120:123], v[84:87], v[48:63]
	s_waitcnt lgkmcnt(3)
	v_mfma_f32_32x32x16_bf16 v[64:79], v[190:193], v[80:83], v[64:79]
	s_waitcnt lgkmcnt(1)
	v_mfma_f32_32x32x16_bf16 v[48:63], v[198:201], v[80:83], v[48:63]
	v_mfma_f32_32x32x16_bf16 v[64:79], v[194:197], v[10:13], v[64:79]
	s_waitcnt lgkmcnt(0)
	v_mfma_f32_32x32x16_bf16 v[48:63], v[202:205], v[10:13], v[48:63]
	s_setprio 0
	v_add_u32_e32 v190, s98, v112
	ds_read_b64_tr_b16 v[194:195], v190 offset:18432
	ds_read_b64_tr_b16 v[196:197], v190 offset:19968
	ds_read_b64_tr_b16 v[198:199], v190 offset:18496
	ds_read_b64_tr_b16 v[200:201], v190 offset:20032
	ds_read_b64_tr_b16 v[202:203], v190 offset:21504
	ds_read_b64_tr_b16 v[204:205], v190 offset:23040
	v_add_u32_e32 v116, 27, v113
	v_cvt_f32_u32_e32 v117, v116
	v_add_u32_e32 v118, -5, v113
	v_cvt_f32_u32_e32 v119, v118
	v_cmp_gt_u32_e32 vcc, s33, v116
	s_nop 3
	v_fma_f32 v64, -v93, v117, v64
	v_add_u32_e32 v116, 26, v113
	v_cndmask_b32_e32 v64, v215, v64, vcc
	v_cvt_f32_u32_e32 v117, v116
	v_cmp_gt_u32_e32 vcc, s33, v118
	v_add_u32_e32 v118, -6, v113
	v_fma_f32 v48, -v93, v119, v48
	v_cvt_f32_u32_e32 v119, v118
	v_cndmask_b32_e32 v48, v215, v48, vcc
	v_fma_f32 v65, -v93, v117, v65
	v_cmp_gt_u32_e32 vcc, s33, v116
	v_fma_f32 v49, -v93, v119, v49
	v_add_u32_e32 v116, 25, v113
	v_cndmask_b32_e32 v65, v215, v65, vcc
	v_cmp_gt_u32_e32 vcc, s33, v118
	v_cvt_f32_u32_e32 v117, v116
	v_fma_f32 v66, -v93, v117, v66
	v_cndmask_b32_e32 v118, v215, v49, vcc
	v_add_u32_e32 v49, -7, v113
	v_cvt_f32_u32_e32 v119, v49
	v_cmp_gt_u32_e32 vcc, s33, v116
	v_add_u32_e32 v116, 24, v113
	v_cvt_f32_u32_e32 v117, v116
	v_cndmask_b32_e32 v66, v215, v66, vcc
	v_fma_f32 v50, -v93, v119, v50
	v_cmp_gt_u32_e32 vcc, s33, v49
	v_add_u32_e32 v49, -8, v113
	v_fma_f32 v67, -v93, v117, v67
	v_cndmask_b32_e32 v119, v215, v50, vcc
	v_cvt_f32_u32_e32 v50, v49
	v_cmp_gt_u32_e32 vcc, s33, v116
	v_fma_f32 v50, -v93, v50, v51
	v_add_u32_e32 v51, 19, v113
	v_cndmask_b32_e32 v67, v215, v67, vcc
	v_cvt_f32_u32_e32 v116, v51
	v_cmp_gt_u32_e32 vcc, s33, v49
	v_add_u32_e32 v49, -13, v113
	v_fma_f32 v68, -v93, v116, v68
	v_cndmask_b32_e32 v117, v215, v50, vcc
	v_cvt_f32_u32_e32 v50, v49
	v_cmp_gt_u32_e32 vcc, s33, v51
	v_add_u32_e32 v51, 18, v113
	v_fma_f32 v50, -v93, v50, v52
	v_cndmask_b32_e32 v116, v215, v68, vcc
	v_cvt_f32_u32_e32 v52, v51
	v_cmp_gt_u32_e32 vcc, s33, v49
	v_add_u32_e32 v49, -14, v113
	v_fma_f32 v52, -v93, v52, v69
	v_cndmask_b32_e32 v120, v215, v50, vcc
	v_cvt_f32_u32_e32 v50, v49
	v_cmp_gt_u32_e32 vcc, s33, v51
	v_add_u32_e32 v51, 17, v113
	v_fma_f32 v50, -v93, v50, v53
	v_cndmask_b32_e32 v69, v215, v52, vcc
	v_cvt_f32_u32_e32 v52, v51
	v_cmp_gt_u32_e32 vcc, s33, v49
	v_add_u32_e32 v49, -15, v113
	v_fma_f32 v52, -v93, v52, v70
	v_cndmask_b32_e32 v121, v215, v50, vcc
	v_cvt_f32_u32_e32 v50, v49
	v_cmp_gt_u32_e32 vcc, s33, v51
	v_add_u32_e32 v51, 16, v113
	v_fma_f32 v50, -v93, v50, v54
	v_cndmask_b32_e32 v122, v215, v52, vcc
	v_cvt_f32_u32_e32 v52, v51
	v_cmp_gt_u32_e32 vcc, s33, v49
	v_add_u32_e32 v49, -16, v113
	v_fma_f32 v52, -v93, v52, v71
	v_cndmask_b32_e32 v123, v215, v50, vcc
	v_cvt_f32_u32_e32 v50, v49
	v_cmp_gt_u32_e32 vcc, s33, v51
	v_add_u32_e32 v51, 11, v113
	v_fma_f32 v50, -v93, v50, v55
	v_cndmask_b32_e32 v71, v215, v52, vcc
	v_cvt_f32_u32_e32 v52, v51
	v_cmp_gt_u32_e32 vcc, s33, v49
	v_subrev_u32_e32 v49, 21, v113
	v_fma_f32 v52, -v93, v52, v72
	v_cndmask_b32_e32 v55, v215, v50, vcc
	v_cvt_f32_u32_e32 v50, v49
	v_cmp_gt_u32_e32 vcc, s33, v51
	v_add_u32_e32 v51, 10, v113
	v_fma_f32 v50, -v93, v50, v56
	v_cndmask_b32_e32 v140, v215, v52, vcc
	v_cvt_f32_u32_e32 v52, v51
	v_cmp_gt_u32_e32 vcc, s33, v49
	v_subrev_u32_e32 v49, 22, v113
	v_fma_f32 v52, -v93, v52, v73
	v_cndmask_b32_e32 v141, v215, v50, vcc
	v_cvt_f32_u32_e32 v50, v49
	v_cmp_gt_u32_e32 vcc, s33, v51
	v_add_u32_e32 v51, 9, v113
	v_fma_f32 v50, -v93, v50, v57
	v_cndmask_b32_e32 v73, v215, v52, vcc
	v_cvt_f32_u32_e32 v52, v51
	v_cmp_gt_u32_e32 vcc, s33, v49
	v_subrev_u32_e32 v49, 23, v113
	v_fma_f32 v52, -v93, v52, v74
	v_cndmask_b32_e32 v57, v215, v50, vcc
	v_cvt_f32_u32_e32 v50, v49
; __device__ __forceinline__ float sum32(float v) { auto rr = __builtin_amdgcn_permlane32_swap(__float_as_uint(v), __float_as_uint(v), false, false); return __uint_as_float(rr[0]) + __uint_as_float(rr[1]); }
; __device__ __forceinline__ float max32(float v) { auto rr = __builtin_amdgcn_permlane32_swap(__float_as_uint(v), __float_as_uint(v), false, false); return fmaxf(__uint_as_float(rr[0]), __uint_as_float(rr[1])); }
; #define EXP2(x) __builtin_amdgcn_exp2f(x)
; __device__ __forceinline__ int crow(int i, int h) { return (i & 3) + 8 * (i >> 2) + 4 * h; }
; template <int MODE, class SF> ...
;     ...
;     for (int i = 0; i < 16; ++i) { s0[i] = sf(s0[i], crow(i, hh)); s1[i] = sf(s1[i], 32 + crow(i, hh)); }
;     if (MODE != 2) {
;         float mloc = fmaxf(s0[0], s1[0]);
; #pragma unroll
;         for (int i = 1; i < 16; ++i) mloc = fmaxf(mloc, fmaxf(s0[i], s1[i]));
;         mloc = max32(mloc);
;         const float mnew = fmaxf(m, mloc), msafe = mnew == -INFINITY ? 0.f : mnew, corr = EXP2(m - msafe);
;         float psum = 0.f;
; #pragma unroll
;         for (int i = 0; i < 16; ++i) { s0[i] = EXP2(s0[i] - msafe); s1[i] = EXP2(s1[i] - msafe); psum += s0[i] + s1[i]; }
;         psum = sum32(psum);
;         l = l * corr + psum; m = mnew;
;         if (MODE == 0 && !__all(corr == 1.f)) {
; #pragma unroll
;             for (int i = 0; i < 16; ++i) { o0[i] *= corr; o1[i] *= corr; } }
	v_cmp_gt_u32_e32 vcc, s33, v51
	v_add_u32_e32 v51, 8, v113
	v_fma_f32 v50, -v93, v50, v58
	v_cndmask_b32_e32 v146, v215, v52, vcc
	v_cvt_f32_u32_e32 v52, v51
	v_cmp_gt_u32_e32 vcc, s33, v49
	v_subrev_u32_e32 v49, 24, v113
	v_fma_f32 v52, -v93, v52, v75
	v_cndmask_b32_e32 v147, v215, v50, vcc
	v_cvt_f32_u32_e32 v50, v49
	v_cmp_gt_u32_e32 vcc, s33, v51
	v_add_u32_e32 v51, 3, v113
	v_fma_f32 v50, -v93, v50, v59
	v_cndmask_b32_e32 v165, v215, v52, vcc
	v_cvt_f32_u32_e32 v52, v51
	v_cmp_gt_u32_e32 vcc, s33, v49
	v_subrev_u32_e32 v49, 29, v113
	v_fma_f32 v52, -v93, v52, v76
	v_cndmask_b32_e32 v167, v215, v50, vcc
	v_cvt_f32_u32_e32 v50, v49
	v_cmp_gt_u32_e32 vcc, s33, v51
	v_add_u32_e32 v51, 2, v113
	v_fma_f32 v50, -v93, v50, v60
	v_cndmask_b32_e32 v169, v215, v52, vcc
	v_cvt_f32_u32_e32 v52, v51
	v_cmp_gt_u32_e32 vcc, s33, v49
	v_subrev_u32_e32 v49, 30, v113
	v_fma_f32 v52, -v93, v52, v77
	v_cndmask_b32_e32 v171, v215, v50, vcc
	v_cvt_f32_u32_e32 v50, v49
	v_cmp_gt_u32_e32 vcc, s33, v51
	v_add_u32_e32 v51, 1, v113
	v_fma_f32 v50, -v93, v50, v61
	v_cndmask_b32_e32 v173, v215, v52, vcc
	v_cvt_f32_u32_e32 v52, v51
	v_cmp_gt_u32_e32 vcc, s33, v49
	v_subrev_u32_e32 v49, 31, v113
	v_fma_f32 v52, -v93, v52, v78
	v_cndmask_b32_e32 v175, v215, v50, vcc
	v_cvt_f32_u32_e32 v50, v49
	v_cmp_gt_u32_e32 vcc, s33, v51
	v_cvt_f32_u32_e32 v51, v113
	v_fma_f32 v50, -v93, v50, v62
	v_cndmask_b32_e32 v177, v215, v52, vcc
	v_cmp_gt_u32_e32 vcc, s33, v49
	v_subrev_u32_e32 v49, 32, v113
	v_fma_f32 v51, -v93, v51, v79
	v_cndmask_b32_e32 v179, v215, v50, vcc
	v_cvt_f32_u32_e32 v50, v49
	v_cmp_gt_u32_e32 vcc, s33, v113
	v_fma_f32 v50, -v93, v50, v63
	s_nop 0
	v_cndmask_b32_e32 v181, v215, v51, vcc
	v_cmp_gt_u32_e32 vcc, s33, v49
	v_max_f32_e32 v49, v65, v118
	v_max3_f32 v49, v64, v48, v49
	v_cndmask_b32_e32 v183, v215, v50, vcc
	v_max_f32_e32 v50, v66, v119
	v_max_f32_e32 v51, v67, v117
	v_max3_f32 v49, v49, v50, v51
	v_max_f32_e32 v50, v116, v120
	v_max_f32_e32 v51, v69, v121
	v_max3_f32 v49, v49, v50, v51
	v_max_f32_e32 v50, v122, v123
	v_max_f32_e32 v51, v71, v55
	v_max3_f32 v49, v49, v50, v51
	v_max_f32_e32 v50, v140, v141
	v_max_f32_e32 v51, v73, v57
	v_max3_f32 v49, v49, v50, v51
	v_max_f32_e32 v50, v146, v147
	v_max_f32_e32 v51, v165, v167
	v_max3_f32 v49, v49, v50, v51
	v_max_f32_e32 v50, v169, v171
	v_max_f32_e32 v51, v173, v175
	v_max3_f32 v49, v49, v50, v51
	v_max_f32_e32 v50, v177, v179
	v_max_f32_e32 v51, v181, v183
	v_max3_f32 v49, v49, v50, v51
	v_mov_b32_e32 v50, v49
	s_nop 1
	v_permlane32_swap_b32_e32 v49, v50
	v_max3_f32 v49, v115, v49, v50
	v_cmp_neq_f32_e32 vcc, s34, v49
	s_nop 1
	v_cndmask_b32_e32 v185, 0, v49, vcc
	v_sub_f32_e32 v50, v64, v185
	v_sub_f32_e32 v48, v48, v185
	v_exp_f32_e32 v62, v50
	v_exp_f32_e32 v50, v48
	v_sub_f32_e32 v48, v65, v185
	v_exp_f32_e32 v64, v48
	v_sub_f32_e32 v48, v118, v185
	v_add_f32_e32 v52, v62, v50
	v_add_f32_e32 v54, 0, v52
	v_sub_f32_e32 v52, v66, v185
	v_exp_f32_e32 v51, v48
	v_exp_f32_e32 v66, v52
	v_sub_f32_e32 v52, v119, v185
	v_exp_f32_e32 v52, v52
	v_add_f32_e32 v56, v64, v51
	v_sub_f32_e32 v53, v67, v185
	v_add_f32_e32 v54, v56, v54
	v_add_f32_e32 v56, v66, v52
	v_exp_f32_e32 v68, v53
	v_sub_f32_e32 v53, v117, v185
	v_add_f32_e32 v58, v56, v54
	v_sub_f32_e32 v54, v116, v185
	v_exp_f32_e32 v53, v53
	v_exp_f32_e32 v70, v54
	v_sub_f32_e32 v54, v120, v185
	v_exp_f32_e32 v54, v54
	v_add_f32_e32 v59, v68, v53
	v_sub_f32_e32 v56, v69, v185
	v_add_f32_e32 v58, v59, v58
	v_add_f32_e32 v59, v70, v54
	v_exp_f32_e32 v72, v56
	v_sub_f32_e32 v56, v121, v185
	v_add_f32_e32 v59, v59, v58
	v_sub_f32_e32 v58, v122, v185
	v_exp_f32_e32 v56, v56
	v_exp_f32_e32 v74, v58
	v_sub_f32_e32 v58, v123, v185
	v_exp_f32_e32 v58, v58
	v_add_f32_e32 v61, v72, v56
	v_sub_f32_e32 v60, v71, v185
	v_sub_f32_e32 v55, v55, v185
	v_exp_f32_e32 v76, v60
	v_exp_f32_e32 v60, v55
	v_add_f32_e32 v55, v61, v59
	v_add_f32_e32 v59, v74, v58
	v_add_f32_e32 v59, v59, v55
	v_sub_f32_e32 v55, v140, v185
	v_exp_f32_e32 v71, v55
	v_sub_f32_e32 v55, v141, v185
	v_exp_f32_e32 v55, v55
	v_add_f32_e32 v61, v76, v60
	v_sub_f32_e32 v63, v73, v185
	v_add_f32_e32 v59, v61, v59
	v_add_f32_e32 v61, v71, v55
	v_exp_f32_e32 v73, v63
	v_sub_f32_e32 v57, v57, v185
	v_add_f32_e32 v63, v61, v59
	v_sub_f32_e32 v59, v146, v185
	v_exp_f32_e32 v57, v57
	v_exp_f32_e32 v75, v59
	v_sub_f32_e32 v59, v147, v185
	v_exp_f32_e32 v59, v59
	v_add_f32_e32 v65, v73, v57
	v_sub_f32_e32 v61, v165, v185
	v_add_f32_e32 v63, v65, v63
	v_add_f32_e32 v65, v75, v59
	v_exp_f32_e32 v77, v61
	v_sub_f32_e32 v61, v167, v185
	v_add_f32_e32 v67, v65, v63
	v_sub_f32_e32 v63, v169, v185
	v_exp_f32_e32 v61, v61
	v_exp_f32_e32 v78, v63
	v_sub_f32_e32 v63, v171, v185
	v_sub_f32_e32 v65, v173, v185
	v_exp_f32_e32 v63, v63
	v_exp_f32_e32 v79, v65
	v_sub_f32_e32 v65, v175, v185
	v_exp_f32_e32 v65, v65
	v_add_f32_e32 v69, v77, v61
	v_add_f32_e32 v67, v69, v67
	v_add_f32_e32 v69, v78, v63
	v_add_f32_e32 v67, v69, v67
	v_add_f32_e32 v69, v79, v65
	v_add_f32_e32 v117, v69, v67
	v_sub_f32_e32 v67, v177, v185
	v_sub_f32_e32 v48, v115, v185
	v_exp_f32_e32 v115, v67
	v_sub_f32_e32 v67, v179, v185
	v_sub_f32_e32 v69, v181, v185
	v_exp_f32_e32 v67, v67
	v_exp_f32_e32 v116, v69
	v_sub_f32_e32 v69, v183, v185
	v_exp_f32_e32 v69, v69
	v_exp_f32_e32 v48, v48
	v_add_f32_e32 v118, v115, v67
	v_add_f32_e32 v117, v118, v117
	v_add_f32_e32 v118, v116, v69
	v_add_f32_e32 v117, v118, v117
	v_mov_b32_e32 v118, v117
	v_cmp_eq_f32_e32 vcc, 1.0, v48
	s_cmp_eq_u64 vcc, exec
	v_permlane32_swap_b32_e32 v117, v118
	s_cbranch_scc1 .LBB0_870
	v_pk_mul_f32 v[30:31], v[30:31], v[48:49] op_sel_hi:[1,0]
	v_pk_mul_f32 v[28:29], v[28:29], v[48:49] op_sel_hi:[1,0]
	v_pk_mul_f32 v[26:27], v[26:27], v[48:49] op_sel_hi:[1,0]
	v_pk_mul_f32 v[24:25], v[24:25], v[48:49] op_sel_hi:[1,0]
	v_pk_mul_f32 v[22:23], v[22:23], v[48:49] op_sel_hi:[1,0]
	v_pk_mul_f32 v[20:21], v[20:21], v[48:49] op_sel_hi:[1,0]
	v_pk_mul_f32 v[18:19], v[18:19], v[48:49] op_sel_hi:[1,0]
	v_pk_mul_f32 v[16:17], v[16:17], v[48:49] op_sel_hi:[1,0]
	v_pk_mul_f32 v[46:47], v[46:47], v[48:49] op_sel_hi:[1,0]
	v_pk_mul_f32 v[44:45], v[44:45], v[48:49] op_sel_hi:[1,0]
	v_pk_mul_f32 v[42:43], v[42:43], v[48:49] op_sel_hi:[1,0]
	v_pk_mul_f32 v[40:41], v[40:41], v[48:49] op_sel_hi:[1,0]
	v_pk_mul_f32 v[38:39], v[38:39], v[48:49] op_sel_hi:[1,0]
	v_pk_mul_f32 v[36:37], v[36:37], v[48:49] op_sel_hi:[1,0]
	v_pk_mul_f32 v[34:35], v[34:35], v[48:49] op_sel_hi:[1,0]
	v_pk_mul_f32 v[32:33], v[32:33], v[48:49] op_sel_hi:[1,0]

; __device__ __forceinline__ void dil_item(const DilArgs& A, int item, LAS unsigned char* lds, int tid) {
;     ...
;     KV_PIPELINE(kb_lo, (cur + 1 <= kb_hi ? cur + 1 : -1), (KVSrc{kp, vp, (long)dil * NP, 64 * id, 0, L}), true, A.g_k,
;         { if (64 * id + 63 >= q_lo - 128 && 64 * id <= q_lo + 31) { const SfDil sf{iq, 64 * id, slope}; attn_block<0>(qf, o0, o1, m, l, ksb, vtb, r, hh, sf, 0.f, 0.f, nullptr, 0, dummy); } });
.LBB0_872:
	s_add_i32 s13, s13, 1
	s_add_i32 s6, s6, 1
	v_subrev_u32_e32 v113, 64, v113
	s_andn2_b64 vcc, exec, s[4:5]
	s_add_i32 s43, s43, 64
	s_cbranch_vccz .LBB0_875
	v_mov_b32_e32 v115, v49
	s_branch .LdilB_top
